# attention loops: removed compiler hazard pads that no longer separate a hazard pair (scalar row-sum chain, between mask blocks)
# baseline (speedup 1.0000x reference)
; template <int DQK, bool MIXA, bool PIPE>
; DI void attn_item(const Params& P, int layer, char* smem, int b, int h, int qt) {
;     ...
;       auto chunk = [&](int kb, int c) __attribute__((always_inline)) {
;         const int s2 = 1 - (c >> 2), e = 3 - (c & 3);
;         const int r0 = 8 * s2 + 2 * e;
;         if (MIXA && c == 4) mrot[kb] <<= 8;
;         f32x2 xv2 = {sacc[kb][r0], sacc[kb][r0 + 1]};
;         xv2 = xv2 * sl2v - mfixv;
;         if (MIXA) {
;           if (near) {
;             const int kl = 16 * (r0 >> 3) + 8 * H + (r0 & 7);
;             const int rel = kc * 64 + 32 * kb + kl - qpos;
;             xv2.x += biasT[rel + 192];
;             xv2.y += biasT[rel + 193];
;           }
;         }
;         f32x2 p2 = {__builtin_amdgcn_exp2f(xv2.x), __builtin_amdgcn_exp2f(xv2.y)};
;         if (MIXA) {
;           float px = p2.x, py = p2.y;
;           asm volatile("v_add_co_u32 %0, vcc, %0, %0\n\tv_cndmask_b32 %1, 0, %1, vcc" : "+v"(mrot[kb]), "+v"(py) : : "vcc");
;           asm volatile("v_add_co_u32 %0, vcc, %0, %0\n\tv_cndmask_b32 %1, 0, %1, vcc" : "+v"(mrot[kb]), "+v"(px) : : "vcc");
;           p2.x = px; p2.y = py;
;         }
;         ls2 += p2;
;         pkw[kb][s2][e] = pk2(p2.x, p2.y);
;       };
;       {
;         int c0 = 0;
; #pragma unroll
;         for (int s = 0; s < NS; ++s) {
;           sacc[1] = __builtin_amdgcn_mfma_f32_32x32x16_bf16(kf[1][s], qf[s], sacc[1], 0, 0, 0);
;           const int cend = (8 * (s + 1)) / NS;
; #pragma unroll
;           for (int c = 0; c < 8; ++c) if (c >= c0 && c < cend) chunk(0, c);
;           c0 = cend;
;           __builtin_amdgcn_sched_barrier(0);
;         }
;       }
;       bf16x8 pf0[2], pf1[2];
; #pragma unroll
;       for (int s2 = 0; s2 < 2; ++s2) { u32x4 t = {pkw[0][s2][0], pkw[0][s2][1], pkw[0][s2][2], pkw[0][s2][3]}; pf0[s2] = __builtin_bit_cast(bf16x8, t); }
; #pragma unroll
;       for (int j = 0; j < 4; ++j) {
;         const int s2 = j >> 1, d = j & 1;
;         o[d] = __builtin_amdgcn_mfma_f32_32x32x16_bf16(vf[d][0][s2], pf0[s2], o[d], 0, 0, 0);
;         chunk(1, 2 * j); chunk(1, 2 * j + 1);
;         __builtin_amdgcn_sched_barrier(0);
;       }
; #pragma unroll
;       for (int s2 = 0; s2 < 2; ++s2) { u32x4 t = {pkw[1][s2][0], pkw[1][s2][1], pkw[1][s2][2], pkw[1][s2][3]}; pf1[s2] = __builtin_bit_cast(bf16x8, t); }
; #pragma unroll
;       for (int j = 0; j < 4; ++j) {
.LBB0_87:
	s_add_i32 s20, s22, 1
	s_movk_i32 s21, 0x5000
	s_add_u32 m0, s21, s32
	s_add_u32 s18, s21, s73
	global_load_lds_dwordx4 v120, s[36:37]
	s_add_u32 m0, m0, 0x400
	s_nop 0
	global_load_lds_dwordx4 v122, s[36:37]
	s_add_u32 m0, m0, 0x400
	s_nop 0
	global_load_lds_dwordx4 v124, s[36:37]
	s_add_u32 m0, s18, 0x3000
	v_cmp_le_i32_e32 vcc, s22, v127
	global_load_lds_dwordx4 v116, s[38:39]
	s_add_u32 m0, s18, 0x3400
	s_nop 0
	global_load_lds_dwordx4 v118, s[38:39]
	s_and_saveexec_b64 s[18:19], vcc
	s_cbranch_execz .Lmla_o86
	ds_read_b128 v[32:35], v168
	ds_read_b128 v[36:39], v168 offset:6144
	ds_read_b128 v[40:43], v170
	ds_read_b128 v[148:151], v170 offset:6144
	ds_read_b128 v[44:47], v172
	ds_read_b128 v[152:155], v172 offset:6144
	ds_read_b128 v[88:91], v174
	ds_read_b128 v[156:159], v174 offset:6144
	ds_read_b128 v[92:95], v176
	ds_read_b128 v[208:211], v176 offset:6144
	ds_read_b128 v[96:99], v244
	ds_read_b128 v[212:215], v244 offset:6144
	s_waitcnt lgkmcnt(0)
	v_mfma_f32_32x32x16_bf16 v[48:63], v[32:35], v[84:87], v[228:243]
	ds_read_b128 v[216:219], v245 offset:12288
	ds_read_b128 v[108:111], v246 offset:12288
	v_mfma_f32_32x32x16_bf16 v[48:63], v[40:43], v[80:83], v[48:63]
	v_mfma_f32_32x32x16_bf16 v[48:63], v[44:47], v[76:79], v[48:63]
	v_mfma_f32_32x32x16_bf16 v[48:63], v[88:91], v[72:75], v[48:63]
	ds_read_b128 v[88:91], v247 offset:12288
	v_mfma_f32_32x32x16_bf16 v[48:63], v[92:95], v[68:71], v[48:63]
	v_mfma_f32_32x32x16_bf16 v[48:63], v[96:99], v[64:67], v[48:63]
	ds_read_b128 v[92:95], v248 offset:12288
	ds_read_b128 v[220:223], v245 offset:16384
	ds_read_b128 v[104:107], v246 offset:16384
	ds_read_b128 v[100:103], v247 offset:16384
	ds_read_b128 v[96:99], v248 offset:16384
	s_nop 6
	v_exp_f32_e32 v32, v62
	v_exp_f32_e32 v33, v63
	v_add_f32_e32 v224, 0, v32
	v_add_f32_e32 v225, 0, v33
	v_cvt_pk_bf16_f32 v63, v32, v33
	v_mfma_f32_32x32x16_bf16 v[32:47], v[36:39], v[84:87], v[228:243]
	v_mfma_f32_32x32x16_bf16 v[32:47], v[148:151], v[80:83], v[32:47]
	v_exp_f32_e32 v60, v60
	v_exp_f32_e32 v61, v61
	v_add_f32_e32 v224, v60, v224
	v_add_f32_e32 v225, v61, v225
	v_cvt_pk_bf16_f32 v62, v60, v61
	v_exp_f32_e32 v58, v58
	v_exp_f32_e32 v59, v59
	v_exp_f32_e32 v56, v56
	v_exp_f32_e32 v57, v57
	v_mfma_f32_32x32x16_bf16 v[32:47], v[152:155], v[76:79], v[32:47]
	v_add_f32_e64 v148, v58, v224
	v_add_f32_e64 v149, v59, v225
	v_cvt_pk_bf16_f32 v61, v58, v59
	v_add_f32_e64 v58, v56, v148
	v_add_f32_e64 v59, v57, v149
	v_cvt_pk_bf16_f32 v60, v56, v57
	v_mfma_f32_32x32x16_bf16 v[32:47], v[156:159], v[72:75], v[32:47]
	v_exp_f32_e32 v54, v54
	v_exp_f32_e32 v55, v55
	v_add_f32_e32 v56, v54, v58
	v_add_f32_e32 v57, v55, v59
	v_cvt_pk_bf16_f32 v55, v54, v55
	v_mfma_f32_32x32x16_bf16 v[32:47], v[208:211], v[68:71], v[32:47]
	v_exp_f32_e32 v52, v52
	v_exp_f32_e32 v53, v53
	v_add_f32_e32 v56, v52, v56
	v_add_f32_e32 v57, v53, v57
	v_cvt_pk_bf16_f32 v54, v52, v53
	v_exp_f32_e32 v50, v50
	v_exp_f32_e32 v51, v51
	v_exp_f32_e32 v48, v48
	v_exp_f32_e32 v49, v49
	v_mfma_f32_32x32x16_bf16 v[32:47], v[212:215], v[64:67], v[32:47]
	v_add_f32_e64 v56, v50, v56
	v_add_f32_e64 v57, v51, v57
	v_cvt_pk_bf16_f32 v53, v50, v51
	v_cvt_pk_bf16_f32 v52, v48, v49
	v_add_f32_e64 v48, v48, v56
	v_add_f32_e64 v49, v49, v57
	s_waitcnt lgkmcnt(0)
	v_mfma_f32_32x32x16_bf16 v[0:15], v[216:219], v[52:55], v[0:15]
	s_nop 3
	v_exp_f32_e32 v46, v46
	v_exp_f32_e32 v47, v47
	v_exp_f32_e32 v44, v44
	v_exp_f32_e32 v45, v45
	v_add_f32_e32 v48, v48, v46
	v_add_f32_e32 v49, v49, v47
	v_cvt_pk_bf16_f32 v47, v46, v47
	v_add_f32_e32 v48, v44, v48
	v_add_f32_e32 v49, v45, v49
	v_cvt_pk_bf16_f32 v46, v44, v45
	v_mfma_f32_32x32x16_bf16 v[16:31], v[220:223], v[52:55], v[16:31]
	v_exp_f32_e32 v42, v42
	v_exp_f32_e32 v43, v43
	v_exp_f32_e32 v40, v40
	v_exp_f32_e32 v41, v41
	v_add_f32_e32 v48, v42, v48
	v_add_f32_e32 v49, v43, v49
	v_cvt_pk_bf16_f32 v45, v42, v43
	v_add_f32_e32 v42, v40, v48
	v_add_f32_e32 v43, v41, v49
	v_cvt_pk_bf16_f32 v44, v40, v41
	v_mfma_f32_32x32x16_bf16 v[0:15], v[108:111], v[60:63], v[0:15]
	v_exp_f32_e32 v38, v38
	v_exp_f32_e32 v39, v39
	v_exp_f32_e32 v36, v36
	v_exp_f32_e32 v37, v37
	v_add_f32_e32 v40, v38, v42
	v_add_f32_e32 v41, v39, v43
	v_cvt_pk_bf16_f32 v39, v38, v39
	v_add_f32_e32 v40, v36, v40
	v_add_f32_e32 v41, v37, v41
	v_cvt_pk_bf16_f32 v38, v36, v37
	v_mfma_f32_32x32x16_bf16 v[16:31], v[104:107], v[60:63], v[16:31]
	v_exp_f32_e32 v34, v34
	v_exp_f32_e32 v35, v35
	v_exp_f32_e32 v32, v32
	v_exp_f32_e32 v33, v33
	v_cvt_pk_bf16_f32 v37, v34, v35
	v_cvt_pk_bf16_f32 v36, v32, v33
	s_nop 1
	v_mfma_f32_32x32x16_bf16 v[0:15], v[88:91], v[36:39], v[0:15]
	v_add_f32_e64 v34, v34, v40
	v_add_f32_e64 v35, v35, v41
	v_add_f32_e64 v32, v32, v34
	v_add_f32_e64 v33, v33, v35
	v_add_f32_e32 v32, v32, v33
	v_add_f32_e32 v126, v126, v32
	v_mfma_f32_32x32x16_bf16 v[16:31], v[100:103], v[36:39], v[16:31]
	v_mfma_f32_32x32x16_bf16 v[0:15], v[92:95], v[44:47], v[0:15]
	v_mfma_f32_32x32x16_bf16 v[16:31], v[96:99], v[44:47], v[16:31]
	s_branch .Lmla_o86

; template <int DQK, bool MIXA, bool PIPE>
; DI void attn_item(const Params& P, int layer, char* smem, int b, int h, int qt) {
;     ...
;       auto chunk = [&](int kb, int c) __attribute__((always_inline)) {
;         const int s2 = 1 - (c >> 2), e = 3 - (c & 3);
;         const int r0 = 8 * s2 + 2 * e;
;         if (MIXA && c == 4) mrot[kb] <<= 8;
;         f32x2 xv2 = {sacc[kb][r0], sacc[kb][r0 + 1]};
;         xv2 = xv2 * sl2v - mfixv;
;         if (MIXA) {
;           if (near) {
;             const int kl = 16 * (r0 >> 3) + 8 * H + (r0 & 7);
;             const int rel = kc * 64 + 32 * kb + kl - qpos;
;             xv2.x += biasT[rel + 192];
;             xv2.y += biasT[rel + 193];
;           }
;         }
;         f32x2 p2 = {__builtin_amdgcn_exp2f(xv2.x), __builtin_amdgcn_exp2f(xv2.y)};
;         if (MIXA) {
;           float px = p2.x, py = p2.y;
;           asm volatile("v_add_co_u32 %0, vcc, %0, %0\n\tv_cndmask_b32 %1, 0, %1, vcc" : "+v"(mrot[kb]), "+v"(py) : : "vcc");
;           asm volatile("v_add_co_u32 %0, vcc, %0, %0\n\tv_cndmask_b32 %1, 0, %1, vcc" : "+v"(mrot[kb]), "+v"(px) : : "vcc");
;           p2.x = px; p2.y = py;
;         }
;         ls2 += p2;
;         pkw[kb][s2][e] = pk2(p2.x, p2.y);
;       };
;       {
;         int c0 = 0;
; #pragma unroll
;         for (int s = 0; s < NS; ++s) {
;           sacc[1] = __builtin_amdgcn_mfma_f32_32x32x16_bf16(kf[1][s], qf[s], sacc[1], 0, 0, 0);
;           const int cend = (8 * (s + 1)) / NS;
; #pragma unroll
;           for (int c = 0; c < 8; ++c) if (c >= c0 && c < cend) chunk(0, c);
;           c0 = cend;
;           __builtin_amdgcn_sched_barrier(0);
;         }
;       }
;       bf16x8 pf0[2], pf1[2];
; #pragma unroll
;       for (int s2 = 0; s2 < 2; ++s2) { u32x4 t = {pkw[0][s2][0], pkw[0][s2][1], pkw[0][s2][2], pkw[0][s2][3]}; pf0[s2] = __builtin_bit_cast(bf16x8, t); }
; #pragma unroll
;       for (int j = 0; j < 4; ++j) {
;         const int s2 = j >> 1, d = j & 1;
;         o[d] = __builtin_amdgcn_mfma_f32_32x32x16_bf16(vf[d][0][s2], pf0[s2], o[d], 0, 0, 0);
;         chunk(1, 2 * j); chunk(1, 2 * j + 1);
;         __builtin_amdgcn_sched_barrier(0);
;       }
; #pragma unroll
;       for (int s2 = 0; s2 < 2; ++s2) { u32x4 t = {pkw[1][s2][0], pkw[1][s2][1], pkw[1][s2][2], pkw[1][s2][3]}; pf1[s2] = __builtin_bit_cast(bf16x8, t); }
; #pragma unroll
;       for (int j = 0; j < 4; ++j) {
.Lmla_o87:
	s_add_i32 s20, s22, 1
	s_mov_b32 s21, 0
	s_add_u32 m0, s21, s32
	s_add_u32 s18, s21, s73
	global_load_lds_dwordx4 v120, s[36:37]
	s_add_u32 m0, m0, 0x400
	s_nop 0
	global_load_lds_dwordx4 v122, s[36:37]
	s_add_u32 m0, m0, 0x400
	s_nop 0
	global_load_lds_dwordx4 v124, s[36:37]
	s_add_u32 m0, s18, 0x3000
	v_cmp_le_i32_e32 vcc, s22, v127
	global_load_lds_dwordx4 v116, s[38:39]
	s_add_u32 m0, s18, 0x3400
	s_nop 0
	global_load_lds_dwordx4 v118, s[38:39]
	s_and_saveexec_b64 s[18:19], vcc
	s_cbranch_execz .LBB0_86
	ds_read_b128 v[32:35], v168 offset:20480
	ds_read_b128 v[36:39], v168 offset:26624
	ds_read_b128 v[40:43], v170 offset:20480
	ds_read_b128 v[148:151], v170 offset:26624
	ds_read_b128 v[44:47], v172 offset:20480
	ds_read_b128 v[152:155], v172 offset:26624
	ds_read_b128 v[88:91], v174 offset:20480
	ds_read_b128 v[156:159], v174 offset:26624
	ds_read_b128 v[92:95], v176 offset:20480
	ds_read_b128 v[208:211], v176 offset:26624
	ds_read_b128 v[96:99], v244 offset:20480
	ds_read_b128 v[212:215], v244 offset:26624
	s_waitcnt lgkmcnt(0)
	v_mfma_f32_32x32x16_bf16 v[48:63], v[32:35], v[84:87], v[228:243]
	ds_read_b128 v[216:219], v245 offset:32768
	ds_read_b128 v[108:111], v246 offset:32768
	v_mfma_f32_32x32x16_bf16 v[48:63], v[40:43], v[80:83], v[48:63]
	v_mfma_f32_32x32x16_bf16 v[48:63], v[44:47], v[76:79], v[48:63]
	v_mfma_f32_32x32x16_bf16 v[48:63], v[88:91], v[72:75], v[48:63]
	ds_read_b128 v[88:91], v247 offset:32768
	v_mfma_f32_32x32x16_bf16 v[48:63], v[92:95], v[68:71], v[48:63]
	v_mfma_f32_32x32x16_bf16 v[48:63], v[96:99], v[64:67], v[48:63]
	ds_read_b128 v[92:95], v248 offset:32768
	ds_read_b128 v[220:223], v245 offset:36864
	ds_read_b128 v[104:107], v246 offset:36864
	ds_read_b128 v[100:103], v247 offset:36864
	ds_read_b128 v[96:99], v248 offset:36864
	s_nop 6
	v_exp_f32_e32 v32, v62
	v_exp_f32_e32 v33, v63
	v_add_f32_e32 v224, 0, v32
	v_add_f32_e32 v225, 0, v33
	v_cvt_pk_bf16_f32 v63, v32, v33
	v_mfma_f32_32x32x16_bf16 v[32:47], v[36:39], v[84:87], v[228:243]
	v_mfma_f32_32x32x16_bf16 v[32:47], v[148:151], v[80:83], v[32:47]
	v_exp_f32_e32 v60, v60
	v_exp_f32_e32 v61, v61
	v_add_f32_e32 v224, v60, v224
	v_add_f32_e32 v225, v61, v225
	v_cvt_pk_bf16_f32 v62, v60, v61
	v_exp_f32_e32 v58, v58
	v_exp_f32_e32 v59, v59
	v_exp_f32_e32 v56, v56
	v_exp_f32_e32 v57, v57
	v_mfma_f32_32x32x16_bf16 v[32:47], v[152:155], v[76:79], v[32:47]
	v_add_f32_e64 v148, v58, v224
	v_add_f32_e64 v149, v59, v225
	v_cvt_pk_bf16_f32 v61, v58, v59
	v_add_f32_e64 v58, v56, v148
	v_add_f32_e64 v59, v57, v149
	v_cvt_pk_bf16_f32 v60, v56, v57
	v_mfma_f32_32x32x16_bf16 v[32:47], v[156:159], v[72:75], v[32:47]
	v_exp_f32_e32 v54, v54
	v_exp_f32_e32 v55, v55
	v_add_f32_e32 v56, v54, v58
	v_add_f32_e32 v57, v55, v59
	v_cvt_pk_bf16_f32 v55, v54, v55
	v_mfma_f32_32x32x16_bf16 v[32:47], v[208:211], v[68:71], v[32:47]
	v_exp_f32_e32 v52, v52
	v_exp_f32_e32 v53, v53
	v_add_f32_e32 v56, v52, v56
	v_add_f32_e32 v57, v53, v57
	v_cvt_pk_bf16_f32 v54, v52, v53
	v_exp_f32_e32 v50, v50
	v_exp_f32_e32 v51, v51
	v_exp_f32_e32 v48, v48
	v_exp_f32_e32 v49, v49
	v_mfma_f32_32x32x16_bf16 v[32:47], v[212:215], v[64:67], v[32:47]
	v_add_f32_e64 v56, v50, v56
	v_add_f32_e64 v57, v51, v57
	v_cvt_pk_bf16_f32 v53, v50, v51
	v_cvt_pk_bf16_f32 v52, v48, v49
	v_add_f32_e64 v48, v48, v56
	v_add_f32_e64 v49, v49, v57
	s_waitcnt lgkmcnt(0)
	v_mfma_f32_32x32x16_bf16 v[0:15], v[216:219], v[52:55], v[0:15]
	s_nop 3
	v_exp_f32_e32 v46, v46
	v_exp_f32_e32 v47, v47
	v_exp_f32_e32 v44, v44
	v_exp_f32_e32 v45, v45
	v_add_f32_e32 v48, v48, v46
	v_add_f32_e32 v49, v49, v47
	v_cvt_pk_bf16_f32 v47, v46, v47
	v_add_f32_e32 v48, v44, v48
	v_add_f32_e32 v49, v45, v49
	v_cvt_pk_bf16_f32 v46, v44, v45
	v_mfma_f32_32x32x16_bf16 v[16:31], v[220:223], v[52:55], v[16:31]
	v_exp_f32_e32 v42, v42
	v_exp_f32_e32 v43, v43
	v_exp_f32_e32 v40, v40
	v_exp_f32_e32 v41, v41
	v_add_f32_e32 v48, v42, v48
	v_add_f32_e32 v49, v43, v49
	v_cvt_pk_bf16_f32 v45, v42, v43
	v_add_f32_e32 v42, v40, v48
	v_add_f32_e32 v43, v41, v49
	v_cvt_pk_bf16_f32 v44, v40, v41
	v_mfma_f32_32x32x16_bf16 v[0:15], v[108:111], v[60:63], v[0:15]
	v_exp_f32_e32 v38, v38
	v_exp_f32_e32 v39, v39
	v_exp_f32_e32 v36, v36
	v_exp_f32_e32 v37, v37
	v_add_f32_e32 v40, v38, v42
	v_add_f32_e32 v41, v39, v43
	v_cvt_pk_bf16_f32 v39, v38, v39
	v_add_f32_e32 v40, v36, v40
	v_add_f32_e32 v41, v37, v41
	v_cvt_pk_bf16_f32 v38, v36, v37
	v_mfma_f32_32x32x16_bf16 v[16:31], v[104:107], v[60:63], v[16:31]
	v_exp_f32_e32 v34, v34
	v_exp_f32_e32 v35, v35
	v_exp_f32_e32 v32, v32
	v_exp_f32_e32 v33, v33
	v_cvt_pk_bf16_f32 v37, v34, v35
	v_cvt_pk_bf16_f32 v36, v32, v33
	s_nop 1
	v_mfma_f32_32x32x16_bf16 v[0:15], v[88:91], v[36:39], v[0:15]
	v_add_f32_e64 v34, v34, v40
	v_add_f32_e64 v35, v35, v41
	v_add_f32_e64 v32, v32, v34
	v_add_f32_e64 v33, v33, v35
	v_add_f32_e32 v32, v32, v33
	v_add_f32_e32 v126, v126, v32
	v_mfma_f32_32x32x16_bf16 v[16:31], v[100:103], v[36:39], v[16:31]
	v_mfma_f32_32x32x16_bf16 v[0:15], v[92:95], v[44:47], v[0:15]
	v_mfma_f32_32x32x16_bf16 v[16:31], v[96:99], v[44:47], v[16:31]
	s_branch .LBB0_86

; template <int DQK, bool MIXA, bool PIPE>
; DI void attn_item(const Params& P, int layer, char* smem, int b, int h, int qt) {
;     ...
;       auto chunk = [&](int kb, int c) __attribute__((always_inline)) {
;         const int s2 = 1 - (c >> 2), e = 3 - (c & 3);
;         const int r0 = 8 * s2 + 2 * e;
;         if (MIXA && c == 4) mrot[kb] <<= 8;
;         f32x2 xv2 = {sacc[kb][r0], sacc[kb][r0 + 1]};
;         xv2 = xv2 * sl2v - mfixv;
;         if (MIXA) {
;           if (near) {
;             const int kl = 16 * (r0 >> 3) + 8 * H + (r0 & 7);
;             const int rel = kc * 64 + 32 * kb + kl - qpos;
;             xv2.x += biasT[rel + 192];
;             xv2.y += biasT[rel + 193];
;           }
;         }
;         f32x2 p2 = {__builtin_amdgcn_exp2f(xv2.x), __builtin_amdgcn_exp2f(xv2.y)};
;         if (MIXA) {
;           float px = p2.x, py = p2.y;
;           asm volatile("v_add_co_u32 %0, vcc, %0, %0\n\tv_cndmask_b32 %1, 0, %1, vcc" : "+v"(mrot[kb]), "+v"(py) : : "vcc");
;           asm volatile("v_add_co_u32 %0, vcc, %0, %0\n\tv_cndmask_b32 %1, 0, %1, vcc" : "+v"(mrot[kb]), "+v"(px) : : "vcc");
;           p2.x = px; p2.y = py;
;         }
;         ls2 += p2;
;         pkw[kb][s2][e] = pk2(p2.x, p2.y);
;       };
;       {
;         int c0 = 0;
; #pragma unroll
;         for (int s = 0; s < NS; ++s) {
;           sacc[1] = __builtin_amdgcn_mfma_f32_32x32x16_bf16(kf[1][s], qf[s], sacc[1], 0, 0, 0);
;           const int cend = (8 * (s + 1)) / NS;
; #pragma unroll
;           for (int c = 0; c < 8; ++c) if (c >= c0 && c < cend) chunk(0, c);
;           c0 = cend;
;           __builtin_amdgcn_sched_barrier(0);
;         }
;       }
;       bf16x8 pf0[2], pf1[2];
; #pragma unroll
;       for (int s2 = 0; s2 < 2; ++s2) { u32x4 t = {pkw[0][s2][0], pkw[0][s2][1], pkw[0][s2][2], pkw[0][s2][3]}; pf0[s2] = __builtin_bit_cast(bf16x8, t); }
; #pragma unroll
;       for (int j = 0; j < 4; ++j) {
;         const int s2 = j >> 1, d = j & 1;
;         o[d] = __builtin_amdgcn_mfma_f32_32x32x16_bf16(vf[d][0][s2], pf0[s2], o[d], 0, 0, 0);
;         chunk(1, 2 * j); chunk(1, 2 * j + 1);
;         __builtin_amdgcn_sched_barrier(0);
;       }
; #pragma unroll
;       for (int s2 = 0; s2 < 2; ++s2) { u32x4 t = {pkw[1][s2][0], pkw[1][s2][1], pkw[1][s2][2], pkw[1][s2][3]}; pf1[s2] = __builtin_bit_cast(bf16x8, t); }
; #pragma unroll
;       for (int j = 0; j < 4; ++j) {
.LBB0_108:
	v_add_f32_e32 v40, 0, v62
	v_add_f32_e32 v41, 0, v63
	v_exp_f32_e32 v33, v33
	v_add_f32_e32 v40, v40, v60
	v_add_f32_e32 v41, v41, v61
	v_exp_f32_e32 v32, v32
	v_add_f32_e32 v40, v40, v58
	v_add_f32_e32 v41, v41, v59
	v_add_co_u32 v100, vcc, v100, v100
	v_cndmask_b32 v33, 0, v33, vcc
	v_add_f32_e32 v40, v40, v56
	v_add_f32_e32 v41, v41, v57
	v_add_co_u32 v100, vcc, v100, v100
	v_cndmask_b32 v32, 0, v32, vcc
	v_add_f32_e32 v40, v40, v54
	v_add_f32_e32 v41, v41, v55
	v_add_f32_e32 v40, v40, v52
	v_add_f32_e32 v41, v41, v53
	v_add_f32_e32 v40, v40, v116
	v_add_f32_e32 v41, v41, v117
	v_add_f32_e32 v40, v40, v118
	v_add_f32_e32 v41, v41, v119
	v_add_f32_e32 v40, v40, v46
	v_add_f32_e32 v41, v41, v47
	v_add_f32_e32 v40, v40, v44
	v_add_f32_e32 v41, v41, v45
	v_add_f32_e32 v40, v40, v48
	v_add_f32_e32 v41, v41, v49
	v_add_f32_e32 v40, v40, v50
	v_add_f32_e32 v41, v41, v51
	v_add_f32_e32 v40, v40, v38
	v_add_f32_e32 v41, v41, v39
	v_add_f32_e32 v40, v40, v36
	v_add_f32_e32 v41, v41, v37
	v_cvt_pk_bf16_f32 v36, v36, v37
	v_add_f32_e32 v42, v40, v34
	v_add_f32_e32 v43, v41, v35
	v_cvt_pk_bf16_f32 v35, v34, v35
	v_cvt_pk_bf16_f32 v37, v38, v39
	v_cvt_pk_bf16_f32 v38, v50, v51
	v_cvt_pk_bf16_f32 v39, v48, v49
	v_cvt_pk_bf16_f32 v40, v44, v45
	v_cvt_pk_bf16_f32 v41, v46, v47
	v_cvt_pk_bf16_f32 v34, v32, v33
	s_nop 1
	v_mfma_f32_32x32x16_bf16 v[0:15], v[80:83], v[34:37], v[0:15]
	v_add_f32_e64 v32, v42, v32
	v_add_f32_e64 v33, v43, v33
	v_add_f32_e32 v32, v32, v33
	v_add_f32_e32 v125, v125, v32
	v_mfma_f32_32x32x16_bf16 v[16:31], v[92:95], v[34:37], v[16:31]
	v_mfma_f32_32x32x16_bf16 v[0:15], v[84:87], v[38:41], v[0:15]
	v_mfma_f32_32x32x16_bf16 v[16:31], v[88:91], v[38:41], v[16:31]

; template <int DQK, bool MIXA, bool PIPE>
; DI void attn_item(const Params& P, int layer, char* smem, int b, int h, int qt) {
;     ...
;       auto chunk = [&](int kb, int c) __attribute__((always_inline)) {
;         const int s2 = 1 - (c >> 2), e = 3 - (c & 3);
;         const int r0 = 8 * s2 + 2 * e;
;         if (MIXA && c == 4) mrot[kb] <<= 8;
;         f32x2 xv2 = {sacc[kb][r0], sacc[kb][r0 + 1]};
;         xv2 = xv2 * sl2v - mfixv;
;         if (MIXA) {
;           if (near) {
;             const int kl = 16 * (r0 >> 3) + 8 * H + (r0 & 7);
;             const int rel = kc * 64 + 32 * kb + kl - qpos;
;             xv2.x += biasT[rel + 192];
;             xv2.y += biasT[rel + 193];
;           }
;         }
;         f32x2 p2 = {__builtin_amdgcn_exp2f(xv2.x), __builtin_amdgcn_exp2f(xv2.y)};
;         if (MIXA) {
;           float px = p2.x, py = p2.y;
;           asm volatile("v_add_co_u32 %0, vcc, %0, %0\n\tv_cndmask_b32 %1, 0, %1, vcc" : "+v"(mrot[kb]), "+v"(py) : : "vcc");
;           asm volatile("v_add_co_u32 %0, vcc, %0, %0\n\tv_cndmask_b32 %1, 0, %1, vcc" : "+v"(mrot[kb]), "+v"(px) : : "vcc");
;           p2.x = px; p2.y = py;
;         }
;         ls2 += p2;
;         pkw[kb][s2][e] = pk2(p2.x, p2.y);
;       };
;       {
;         int c0 = 0;
; #pragma unroll
;         for (int s = 0; s < NS; ++s) {
;           sacc[1] = __builtin_amdgcn_mfma_f32_32x32x16_bf16(kf[1][s], qf[s], sacc[1], 0, 0, 0);
;           const int cend = (8 * (s + 1)) / NS;
; #pragma unroll
;           for (int c = 0; c < 8; ++c) if (c >= c0 && c < cend) chunk(0, c);
;           c0 = cend;
;           __builtin_amdgcn_sched_barrier(0);
;         }
;       }
;       bf16x8 pf0[2], pf1[2];
; #pragma unroll
;       for (int s2 = 0; s2 < 2; ++s2) { u32x4 t = {pkw[0][s2][0], pkw[0][s2][1], pkw[0][s2][2], pkw[0][s2][3]}; pf0[s2] = __builtin_bit_cast(bf16x8, t); }
; #pragma unroll
;       for (int j = 0; j < 4; ++j) {
;         const int s2 = j >> 1, d = j & 1;
;         o[d] = __builtin_amdgcn_mfma_f32_32x32x16_bf16(vf[d][0][s2], pf0[s2], o[d], 0, 0, 0);
;         chunk(1, 2 * j); chunk(1, 2 * j + 1);
;         __builtin_amdgcn_sched_barrier(0);
;       }
; #pragma unroll
;       for (int s2 = 0; s2 < 2; ++s2) { u32x4 t = {pkw[1][s2][0], pkw[1][s2][1], pkw[1][s2][2], pkw[1][s2][3]}; pf1[s2] = __builtin_bit_cast(bf16x8, t); }
; #pragma unroll
;       for (int j = 0; j < 4; ++j) {
.Lmixa_back_1:
	v_exp_f32_e32 v61, v61
	v_exp_f32_e32 v60, v60
	v_mfma_f32_32x32x16_bf16 v[32:47], v[32:35], v[76:79], v[228:243]
	v_add_co_u32 v166, vcc, v166, v166
	v_cndmask_b32 v61, 0, v61, vcc
	v_add_co_u32 v166, vcc, v166, v166
	v_cndmask_b32 v60, 0, v60, vcc
	s_cbranch_scc1 .Lmixa_near_2

; template <int DQK, bool MIXA, bool PIPE>
; DI void attn_item(const Params& P, int layer, char* smem, int b, int h, int qt) {
;     ...
;       auto chunk = [&](int kb, int c) __attribute__((always_inline)) {
;         const int s2 = 1 - (c >> 2), e = 3 - (c & 3);
;         const int r0 = 8 * s2 + 2 * e;
;         if (MIXA && c == 4) mrot[kb] <<= 8;
;         f32x2 xv2 = {sacc[kb][r0], sacc[kb][r0 + 1]};
;         xv2 = xv2 * sl2v - mfixv;
;         if (MIXA) {
;           if (near) {
;             const int kl = 16 * (r0 >> 3) + 8 * H + (r0 & 7);
;             const int rel = kc * 64 + 32 * kb + kl - qpos;
;             xv2.x += biasT[rel + 192];
;             xv2.y += biasT[rel + 193];
;           }
;         }
;         f32x2 p2 = {__builtin_amdgcn_exp2f(xv2.x), __builtin_amdgcn_exp2f(xv2.y)};
;         if (MIXA) {
;           float px = p2.x, py = p2.y;
;           asm volatile("v_add_co_u32 %0, vcc, %0, %0\n\tv_cndmask_b32 %1, 0, %1, vcc" : "+v"(mrot[kb]), "+v"(py) : : "vcc");
;           asm volatile("v_add_co_u32 %0, vcc, %0, %0\n\tv_cndmask_b32 %1, 0, %1, vcc" : "+v"(mrot[kb]), "+v"(px) : : "vcc");
;           p2.x = px; p2.y = py;
;         }
;         ls2 += p2;
;         pkw[kb][s2][e] = pk2(p2.x, p2.y);
;       };
;       {
;         int c0 = 0;
; #pragma unroll
;         for (int s = 0; s < NS; ++s) {
;           sacc[1] = __builtin_amdgcn_mfma_f32_32x32x16_bf16(kf[1][s], qf[s], sacc[1], 0, 0, 0);
;           const int cend = (8 * (s + 1)) / NS;
; #pragma unroll
;           for (int c = 0; c < 8; ++c) if (c >= c0 && c < cend) chunk(0, c);
;           c0 = cend;
;           __builtin_amdgcn_sched_barrier(0);
;         }
;       }
;       bf16x8 pf0[2], pf1[2];
; #pragma unroll
;       for (int s2 = 0; s2 < 2; ++s2) { u32x4 t = {pkw[0][s2][0], pkw[0][s2][1], pkw[0][s2][2], pkw[0][s2][3]}; pf0[s2] = __builtin_bit_cast(bf16x8, t); }
; #pragma unroll
;       for (int j = 0; j < 4; ++j) {
;         const int s2 = j >> 1, d = j & 1;
;         o[d] = __builtin_amdgcn_mfma_f32_32x32x16_bf16(vf[d][0][s2], pf0[s2], o[d], 0, 0, 0);
;         chunk(1, 2 * j); chunk(1, 2 * j + 1);
;         __builtin_amdgcn_sched_barrier(0);
;       }
; #pragma unroll
;       for (int s2 = 0; s2 < 2; ++s2) { u32x4 t = {pkw[1][s2][0], pkw[1][s2][1], pkw[1][s2][2], pkw[1][s2][3]}; pf1[s2] = __builtin_bit_cast(bf16x8, t); }
; #pragma unroll
;       for (int j = 0; j < 4; ++j) {
.Lmixa_back_3:
	v_mfma_f32_32x32x16_bf16 v[32:47], v[120:123], v[72:75], v[32:47]
	v_exp_f32_e32 v57, v57
	v_exp_f32_e32 v56, v56
	v_add_co_u32 v166, vcc, v166, v166
	v_cndmask_b32 v57, 0, v57, vcc
	v_add_co_u32 v166, vcc, v166, v166
	v_cndmask_b32 v56, 0, v56, vcc
	s_cbranch_scc1 .Lmixa_near_4

; template <int DQK, bool MIXA, bool PIPE>
; DI void attn_item(const Params& P, int layer, char* smem, int b, int h, int qt) {
;     ...
;       auto chunk = [&](int kb, int c) __attribute__((always_inline)) {
;         const int s2 = 1 - (c >> 2), e = 3 - (c & 3);
;         const int r0 = 8 * s2 + 2 * e;
;         if (MIXA && c == 4) mrot[kb] <<= 8;
;         f32x2 xv2 = {sacc[kb][r0], sacc[kb][r0 + 1]};
;         xv2 = xv2 * sl2v - mfixv;
;         if (MIXA) {
;           if (near) {
;             const int kl = 16 * (r0 >> 3) + 8 * H + (r0 & 7);
;             const int rel = kc * 64 + 32 * kb + kl - qpos;
;             xv2.x += biasT[rel + 192];
;             xv2.y += biasT[rel + 193];
;           }
;         }
;         f32x2 p2 = {__builtin_amdgcn_exp2f(xv2.x), __builtin_amdgcn_exp2f(xv2.y)};
;         if (MIXA) {
;           float px = p2.x, py = p2.y;
;           asm volatile("v_add_co_u32 %0, vcc, %0, %0\n\tv_cndmask_b32 %1, 0, %1, vcc" : "+v"(mrot[kb]), "+v"(py) : : "vcc");
;           asm volatile("v_add_co_u32 %0, vcc, %0, %0\n\tv_cndmask_b32 %1, 0, %1, vcc" : "+v"(mrot[kb]), "+v"(px) : : "vcc");
;           p2.x = px; p2.y = py;
;         }
;         ls2 += p2;
;         pkw[kb][s2][e] = pk2(p2.x, p2.y);
;       };
;       {
;         int c0 = 0;
; #pragma unroll
;         for (int s = 0; s < NS; ++s) {
;           sacc[1] = __builtin_amdgcn_mfma_f32_32x32x16_bf16(kf[1][s], qf[s], sacc[1], 0, 0, 0);
;           const int cend = (8 * (s + 1)) / NS;
; #pragma unroll
;           for (int c = 0; c < 8; ++c) if (c >= c0 && c < cend) chunk(0, c);
;           c0 = cend;
;           __builtin_amdgcn_sched_barrier(0);
;         }
;       }
;       bf16x8 pf0[2], pf1[2];
; #pragma unroll
;       for (int s2 = 0; s2 < 2; ++s2) { u32x4 t = {pkw[0][s2][0], pkw[0][s2][1], pkw[0][s2][2], pkw[0][s2][3]}; pf0[s2] = __builtin_bit_cast(bf16x8, t); }
; #pragma unroll
;       for (int j = 0; j < 4; ++j) {
;         const int s2 = j >> 1, d = j & 1;
;         o[d] = __builtin_amdgcn_mfma_f32_32x32x16_bf16(vf[d][0][s2], pf0[s2], o[d], 0, 0, 0);
;         chunk(1, 2 * j); chunk(1, 2 * j + 1);
;         __builtin_amdgcn_sched_barrier(0);
;       }
; #pragma unroll
;       for (int s2 = 0; s2 < 2; ++s2) { u32x4 t = {pkw[1][s2][0], pkw[1][s2][1], pkw[1][s2][2], pkw[1][s2][3]}; pf1[s2] = __builtin_bit_cast(bf16x8, t); }
; #pragma unroll
;       for (int j = 0; j < 4; ++j) {
.Lmixa_back_5:
	v_mfma_f32_32x32x16_bf16 v[32:47], v[116:119], v[68:71], v[32:47]
	v_exp_f32_e32 v53, v53
	v_exp_f32_e32 v52, v52
	v_add_co_u32 v120, vcc, v120, v120
	v_cndmask_b32 v53, 0, v53, vcc
	v_add_co_u32 v120, vcc, v120, v120
	v_cndmask_b32 v52, 0, v52, vcc
	s_cbranch_scc1 .Lmixa_near_6

; template <int DQK, bool MIXA, bool PIPE>
; DI void attn_item(const Params& P, int layer, char* smem, int b, int h, int qt) {
;     ...
;       auto chunk = [&](int kb, int c) __attribute__((always_inline)) {
;         const int s2 = 1 - (c >> 2), e = 3 - (c & 3);
;         const int r0 = 8 * s2 + 2 * e;
;         if (MIXA && c == 4) mrot[kb] <<= 8;
;         f32x2 xv2 = {sacc[kb][r0], sacc[kb][r0 + 1]};
;         xv2 = xv2 * sl2v - mfixv;
;         if (MIXA) {
;           if (near) {
;             const int kl = 16 * (r0 >> 3) + 8 * H + (r0 & 7);
;             const int rel = kc * 64 + 32 * kb + kl - qpos;
;             xv2.x += biasT[rel + 192];
;             xv2.y += biasT[rel + 193];
;           }
;         }
;         f32x2 p2 = {__builtin_amdgcn_exp2f(xv2.x), __builtin_amdgcn_exp2f(xv2.y)};
;         if (MIXA) {
;           float px = p2.x, py = p2.y;
;           asm volatile("v_add_co_u32 %0, vcc, %0, %0\n\tv_cndmask_b32 %1, 0, %1, vcc" : "+v"(mrot[kb]), "+v"(py) : : "vcc");
;           asm volatile("v_add_co_u32 %0, vcc, %0, %0\n\tv_cndmask_b32 %1, 0, %1, vcc" : "+v"(mrot[kb]), "+v"(px) : : "vcc");
;           p2.x = px; p2.y = py;
;         }
;         ls2 += p2;
;         pkw[kb][s2][e] = pk2(p2.x, p2.y);
;       };
;       {
;         int c0 = 0;
; #pragma unroll
;         for (int s = 0; s < NS; ++s) {
;           sacc[1] = __builtin_amdgcn_mfma_f32_32x32x16_bf16(kf[1][s], qf[s], sacc[1], 0, 0, 0);
;           const int cend = (8 * (s + 1)) / NS;
; #pragma unroll
;           for (int c = 0; c < 8; ++c) if (c >= c0 && c < cend) chunk(0, c);
;           c0 = cend;
;           __builtin_amdgcn_sched_barrier(0);
;         }
;       }
;       bf16x8 pf0[2], pf1[2];
; #pragma unroll
;       for (int s2 = 0; s2 < 2; ++s2) { u32x4 t = {pkw[0][s2][0], pkw[0][s2][1], pkw[0][s2][2], pkw[0][s2][3]}; pf0[s2] = __builtin_bit_cast(bf16x8, t); }
; #pragma unroll
;       for (int j = 0; j < 4; ++j) {
;         const int s2 = j >> 1, d = j & 1;
;         o[d] = __builtin_amdgcn_mfma_f32_32x32x16_bf16(vf[d][0][s2], pf0[s2], o[d], 0, 0, 0);
;         chunk(1, 2 * j); chunk(1, 2 * j + 1);
;         __builtin_amdgcn_sched_barrier(0);
;       }
; #pragma unroll
;       for (int s2 = 0; s2 < 2; ++s2) { u32x4 t = {pkw[1][s2][0], pkw[1][s2][1], pkw[1][s2][2], pkw[1][s2][3]}; pf1[s2] = __builtin_bit_cast(bf16x8, t); }
; #pragma unroll
;       for (int j = 0; j < 4; ++j) {
.Lmixa_back_7:
	v_mfma_f32_32x32x16_bf16 v[32:47], v[108:111], v[64:67], v[32:47]
	v_exp_f32_e32 v119, v49
	v_exp_f32_e32 v118, v48
	v_add_co_u32 v120, vcc, v120, v120
	v_cndmask_b32 v119, 0, v119, vcc
	v_cvt_pk_bf16_f32 v49, v116, v117
	v_cvt_pk_bf16_f32 v50, v52, v53
	v_cvt_pk_bf16_f32 v51, v54, v55
	v_add_co_u32 v120, vcc, v120, v120
	v_cndmask_b32 v118, 0, v118, vcc
	v_cvt_pk_bf16_f32 v48, v118, v119
	s_waitcnt lgkmcnt(0)
	s_nop 0
	v_mfma_f32_32x32x16_bf16 v[0:15], v[112:115], v[48:51], v[0:15]
	s_cbranch_scc1 .Lmixa_near_8

; template <int DQK, bool MIXA, bool PIPE>
; DI void attn_item(const Params& P, int layer, char* smem, int b, int h, int qt) {
;     ...
;       auto chunk = [&](int kb, int c) __attribute__((always_inline)) {
;         const int s2 = 1 - (c >> 2), e = 3 - (c & 3);
;         const int r0 = 8 * s2 + 2 * e;
;         if (MIXA && c == 4) mrot[kb] <<= 8;
;         f32x2 xv2 = {sacc[kb][r0], sacc[kb][r0 + 1]};
;         xv2 = xv2 * sl2v - mfixv;
;         if (MIXA) {
;           if (near) {
;             const int kl = 16 * (r0 >> 3) + 8 * H + (r0 & 7);
;             const int rel = kc * 64 + 32 * kb + kl - qpos;
;             xv2.x += biasT[rel + 192];
;             xv2.y += biasT[rel + 193];
;           }
;         }
;         f32x2 p2 = {__builtin_amdgcn_exp2f(xv2.x), __builtin_amdgcn_exp2f(xv2.y)};
;         if (MIXA) {
;           float px = p2.x, py = p2.y;
;           asm volatile("v_add_co_u32 %0, vcc, %0, %0\n\tv_cndmask_b32 %1, 0, %1, vcc" : "+v"(mrot[kb]), "+v"(py) : : "vcc");
;           asm volatile("v_add_co_u32 %0, vcc, %0, %0\n\tv_cndmask_b32 %1, 0, %1, vcc" : "+v"(mrot[kb]), "+v"(px) : : "vcc");
;           p2.x = px; p2.y = py;
;         }
;         ls2 += p2;
;         pkw[kb][s2][e] = pk2(p2.x, p2.y);
;       };
;       {
;         int c0 = 0;
; #pragma unroll
;         for (int s = 0; s < NS; ++s) {
;           sacc[1] = __builtin_amdgcn_mfma_f32_32x32x16_bf16(kf[1][s], qf[s], sacc[1], 0, 0, 0);
;           const int cend = (8 * (s + 1)) / NS;
; #pragma unroll
;           for (int c = 0; c < 8; ++c) if (c >= c0 && c < cend) chunk(0, c);
;           c0 = cend;
;           __builtin_amdgcn_sched_barrier(0);
;         }
;       }
;       bf16x8 pf0[2], pf1[2];
; #pragma unroll
;       for (int s2 = 0; s2 < 2; ++s2) { u32x4 t = {pkw[0][s2][0], pkw[0][s2][1], pkw[0][s2][2], pkw[0][s2][3]}; pf0[s2] = __builtin_bit_cast(bf16x8, t); }
; #pragma unroll
;       for (int j = 0; j < 4; ++j) {
;         const int s2 = j >> 1, d = j & 1;
;         o[d] = __builtin_amdgcn_mfma_f32_32x32x16_bf16(vf[d][0][s2], pf0[s2], o[d], 0, 0, 0);
;         chunk(1, 2 * j); chunk(1, 2 * j + 1);
;         __builtin_amdgcn_sched_barrier(0);
;       }
; #pragma unroll
;       for (int s2 = 0; s2 < 2; ++s2) { u32x4 t = {pkw[1][s2][0], pkw[1][s2][1], pkw[1][s2][2], pkw[1][s2][3]}; pf1[s2] = __builtin_bit_cast(bf16x8, t); }
; #pragma unroll
;       for (int j = 0; j < 4; ++j) {
.Lmixa_back_9:
	v_exp_f32_e32 v45, v45
	v_exp_f32_e32 v44, v44
	v_add_co_u32 v108, vcc, v108, v108
	v_cndmask_b32 v45, 0, v45, vcc
	v_add_co_u32 v108, vcc, v108, v108
	v_cndmask_b32 v44, 0, v44, vcc
	v_mfma_f32_32x32x16_bf16 v[16:31], v[104:107], v[48:51], v[16:31]
	s_cbranch_scc1 .Lmixa_near_10

; template <int DQK, bool MIXA, bool PIPE>
; DI void attn_item(const Params& P, int layer, char* smem, int b, int h, int qt) {
;     ...
;       auto chunk = [&](int kb, int c) __attribute__((always_inline)) {
;         const int s2 = 1 - (c >> 2), e = 3 - (c & 3);
;         const int r0 = 8 * s2 + 2 * e;
;         if (MIXA && c == 4) mrot[kb] <<= 8;
;         f32x2 xv2 = {sacc[kb][r0], sacc[kb][r0 + 1]};
;         xv2 = xv2 * sl2v - mfixv;
;         if (MIXA) {
;           if (near) {
;             const int kl = 16 * (r0 >> 3) + 8 * H + (r0 & 7);
;             const int rel = kc * 64 + 32 * kb + kl - qpos;
;             xv2.x += biasT[rel + 192];
;             xv2.y += biasT[rel + 193];
;           }
;         }
;         f32x2 p2 = {__builtin_amdgcn_exp2f(xv2.x), __builtin_amdgcn_exp2f(xv2.y)};
;         if (MIXA) {
;           float px = p2.x, py = p2.y;
;           asm volatile("v_add_co_u32 %0, vcc, %0, %0\n\tv_cndmask_b32 %1, 0, %1, vcc" : "+v"(mrot[kb]), "+v"(py) : : "vcc");
;           asm volatile("v_add_co_u32 %0, vcc, %0, %0\n\tv_cndmask_b32 %1, 0, %1, vcc" : "+v"(mrot[kb]), "+v"(px) : : "vcc");
;           p2.x = px; p2.y = py;
;         }
;         ls2 += p2;
;         pkw[kb][s2][e] = pk2(p2.x, p2.y);
;       };
;       {
;         int c0 = 0;
; #pragma unroll
;         for (int s = 0; s < NS; ++s) {
;           sacc[1] = __builtin_amdgcn_mfma_f32_32x32x16_bf16(kf[1][s], qf[s], sacc[1], 0, 0, 0);
;           const int cend = (8 * (s + 1)) / NS;
; #pragma unroll
;           for (int c = 0; c < 8; ++c) if (c >= c0 && c < cend) chunk(0, c);
;           c0 = cend;
;           __builtin_amdgcn_sched_barrier(0);
;         }
;       }
;       bf16x8 pf0[2], pf1[2];
; #pragma unroll
;       for (int s2 = 0; s2 < 2; ++s2) { u32x4 t = {pkw[0][s2][0], pkw[0][s2][1], pkw[0][s2][2], pkw[0][s2][3]}; pf0[s2] = __builtin_bit_cast(bf16x8, t); }
; #pragma unroll
;       for (int j = 0; j < 4; ++j) {
;         const int s2 = j >> 1, d = j & 1;
;         o[d] = __builtin_amdgcn_mfma_f32_32x32x16_bf16(vf[d][0][s2], pf0[s2], o[d], 0, 0, 0);
;         chunk(1, 2 * j); chunk(1, 2 * j + 1);
;         __builtin_amdgcn_sched_barrier(0);
;       }
; #pragma unroll
;       for (int s2 = 0; s2 < 2; ++s2) { u32x4 t = {pkw[1][s2][0], pkw[1][s2][1], pkw[1][s2][2], pkw[1][s2][3]}; pf1[s2] = __builtin_bit_cast(bf16x8, t); }
; #pragma unroll
;       for (int j = 0; j < 4; ++j) {
.Lmixa_back_11:
	v_exp_f32_e32 v51, v41
	v_exp_f32_e32 v50, v40
	v_cvt_pk_bf16_f32 v40, v56, v57
	v_cvt_pk_bf16_f32 v41, v58, v59
	v_cvt_pk_bf16_f32 v42, v60, v61
	v_cvt_pk_bf16_f32 v43, v62, v63
	v_add_co_u32 v108, vcc, v108, v108
	v_cndmask_b32 v51, 0, v51, vcc
	v_add_co_u32 v108, vcc, v108, v108
	v_cndmask_b32 v50, 0, v50, vcc
	v_mfma_f32_32x32x16_bf16 v[0:15], v[100:103], v[40:43], v[0:15]
	s_cbranch_scc1 .Lmixa_near_12

; template <int DQK, bool MIXA, bool PIPE>
; DI void attn_item(const Params& P, int layer, char* smem, int b, int h, int qt) {
;     ...
;       auto chunk = [&](int kb, int c) __attribute__((always_inline)) {
;         const int s2 = 1 - (c >> 2), e = 3 - (c & 3);
;         const int r0 = 8 * s2 + 2 * e;
;         if (MIXA && c == 4) mrot[kb] <<= 8;
;         f32x2 xv2 = {sacc[kb][r0], sacc[kb][r0 + 1]};
;         xv2 = xv2 * sl2v - mfixv;
;         if (MIXA) {
;           if (near) {
;             const int kl = 16 * (r0 >> 3) + 8 * H + (r0 & 7);
;             const int rel = kc * 64 + 32 * kb + kl - qpos;
;             xv2.x += biasT[rel + 192];
;             xv2.y += biasT[rel + 193];
;           }
;         }
;         f32x2 p2 = {__builtin_amdgcn_exp2f(xv2.x), __builtin_amdgcn_exp2f(xv2.y)};
;         if (MIXA) {
;           float px = p2.x, py = p2.y;
;           asm volatile("v_add_co_u32 %0, vcc, %0, %0\n\tv_cndmask_b32 %1, 0, %1, vcc" : "+v"(mrot[kb]), "+v"(py) : : "vcc");
;           asm volatile("v_add_co_u32 %0, vcc, %0, %0\n\tv_cndmask_b32 %1, 0, %1, vcc" : "+v"(mrot[kb]), "+v"(px) : : "vcc");
;           p2.x = px; p2.y = py;
;         }
;         ls2 += p2;
;         pkw[kb][s2][e] = pk2(p2.x, p2.y);
;       };
;       {
;         int c0 = 0;
; #pragma unroll
;         for (int s = 0; s < NS; ++s) {
;           sacc[1] = __builtin_amdgcn_mfma_f32_32x32x16_bf16(kf[1][s], qf[s], sacc[1], 0, 0, 0);
;           const int cend = (8 * (s + 1)) / NS;
; #pragma unroll
;           for (int c = 0; c < 8; ++c) if (c >= c0 && c < cend) chunk(0, c);
;           c0 = cend;
;           __builtin_amdgcn_sched_barrier(0);
;         }
;       }
;       bf16x8 pf0[2], pf1[2];
; #pragma unroll
;       for (int s2 = 0; s2 < 2; ++s2) { u32x4 t = {pkw[0][s2][0], pkw[0][s2][1], pkw[0][s2][2], pkw[0][s2][3]}; pf0[s2] = __builtin_bit_cast(bf16x8, t); }
; #pragma unroll
;       for (int j = 0; j < 4; ++j) {
;         const int s2 = j >> 1, d = j & 1;
;         o[d] = __builtin_amdgcn_mfma_f32_32x32x16_bf16(vf[d][0][s2], pf0[s2], o[d], 0, 0, 0);
;         chunk(1, 2 * j); chunk(1, 2 * j + 1);
;         __builtin_amdgcn_sched_barrier(0);
;       }
; #pragma unroll
;       for (int s2 = 0; s2 < 2; ++s2) { u32x4 t = {pkw[1][s2][0], pkw[1][s2][1], pkw[1][s2][2], pkw[1][s2][3]}; pf1[s2] = __builtin_bit_cast(bf16x8, t); }
; #pragma unroll
;       for (int j = 0; j < 4; ++j) {
.Lmixa_back_13:
	v_exp_f32_e32 v37, v37
	v_exp_f32_e32 v36, v36
	v_add_co_u32 v100, vcc, v100, v100
	v_cndmask_b32 v37, 0, v37, vcc
	v_add_co_u32 v100, vcc, v100, v100
	v_cndmask_b32 v36, 0, v36, vcc
	v_mfma_f32_32x32x16_bf16 v[16:31], v[96:99], v[40:43], v[16:31]
	s_cbranch_scc1 .Lmixa_near_14
